# attention item: Q fragments and first K/V tile requested before the log-forget scan (one exposed latency per item instead of two); v-sweep slice-change gamma/beta reload no longer drains vmcnt(0)
# baseline (speedup 1.0000x reference)
.LBB0_931:
	s_mov_b64 s[4:5], 0
	s_add_i32 s8, s3, 0xffffff80
	s_add_u32 s4, s96, s4
	s_addc_u32 s5, s97, s5
	s_and_b32 s9, s8, 0xff
	v_mov_b32_e32 v6, v176
	s_lshl_b32 s6, s9, 13
	s_add_u32 s6, s4, s6
	v_lshlrev_b32_e32 v4, 2, v6
	s_addc_u32 s7, s5, 0
	v_ashrrev_i32_e32 v5, 31, v4
	v_lshl_add_u64 v[0:1], v[4:5], 2, s[6:7]
	s_mov_b32 s6, 0x1a00000
	v_add_co_u32_e32 v0, vcc, s6, v0
	s_nop 1
	v_addc_co_u32_e32 v1, vcc, 0, v1, vcc
	v_ashrrev_i32_e32 v102, 6, v6
	s_andn2_b32 s6, 0x700, s8
	v_and_b32_e32 v103, 31, v6
	v_lshl_add_u32 v102, v102, 5, s6
	s_lshl_b32 s6, s8, 8
	v_or_b32_e32 v102, v102, v103
	s_and_b32 s10, s6, 0xf800
	s_lshl_b32 s6, s8, 6
	v_add_u32_e32 v102, s10, v102
	s_and_b32 s11, s6, 0x1c0
	v_ashrrev_i32_e32 v103, 31, v102
	s_lshl_b32 s88, s11, 1
	v_lshlrev_b64 v[102:103], 9, v[102:103]
	v_bfe_u32 v104, v6, 5, 1
	v_or_b32_e32 v102, s11, v102
	v_lshlrev_b32_e32 v104, 4, v104
	v_mov_b32_e32 v105, 0
	v_lshl_add_u64 v[102:103], v[102:103], 1, s[4:5]
	s_mov_b64 s[6:7], 0x30000000
	v_lshl_add_u64 v[102:103], v[102:103], 0, v[104:105]
	v_ashrrev_i32_e32 v106, 3, v6
	v_lshl_add_u64 v[102:103], v[102:103], 0, s[6:7]
	v_add_u32_e32 v108, s10, v106
	global_load_dwordx4 v[72:75], v[102:103], off
	global_load_dwordx4 v[64:67], v[102:103], off offset:32
	global_load_dwordx4 v[68:71], v[102:103], off offset:64
	global_load_dwordx4 v[76:79], v[102:103], off offset:96
	v_ashrrev_i32_e32 v109, 31, v108
	v_lshlrev_b32_e32 v104, 4, v6
	v_lshlrev_b64 v[108:109], 10, v[108:109]
	v_and_b32_e32 v104, 0x70, v104
	v_lshl_add_u64 v[108:109], s[4:5], 0, v[108:109]
	s_mov_b64 s[6:7], 0x24000000
	v_lshl_add_u64 v[108:109], v[108:109], 0, s[88:89]
	v_ashrrev_i32_e32 v107, 31, v106
	v_lshl_add_u64 v[108:109], v[108:109], 0, v[104:105]
	v_lshlrev_b64 v[106:107], 12, v[106:107]
	v_lshl_add_u64 v[110:111], v[108:109], 0, s[6:7]
	s_lshl_b32 s6, s9, 18
	global_load_dwordx4 v[80:83], v[110:111], off
	s_add_u32 s6, s4, s6
	s_addc_u32 s7, s5, 0
	v_lshl_add_u64 v[106:107], s[6:7], 0, v[106:107]
	s_mov_b64 s[6:7], 0x34000000
	v_lshl_add_u64 v[106:107], v[106:107], 0, v[104:105]
	s_nop 0
	v_lshl_add_u64 v[106:107], v[106:107], 0, s[6:7]
	global_load_dwordx4 v[84:87], v[106:107], off
	s_barrier
	global_load_dwordx4 v[0:3], v[0:1], off
	v_cmp_lt_i32_e32 vcc, v181, v180
	s_waitcnt vmcnt(0)
	v_add_f32_e32 v1, v0, v1
	v_cndmask_b32_e32 v5, v181, v171, vcc
	v_add_f32_e32 v2, v2, v1
	v_lshlrev_b32_e32 v5, 2, v5
	v_add_f32_e32 v3, v3, v2
	ds_bpermute_b32 v5, v5, v3
	v_cmp_lt_i32_e32 vcc, v182, v180
	s_waitcnt lgkmcnt(0)
	v_add_f32_e32 v5, v3, v5
	v_cndmask_b32_e32 v7, v182, v171, vcc
	v_lshlrev_b32_e32 v8, 2, v7
	v_and_b32_e32 v7, 63, v6
	v_cmp_eq_u32_e32 vcc, 0, v7
	s_nop 1
	v_cndmask_b32_e32 v5, v5, v3, vcc
	ds_bpermute_b32 v8, v8, v5
	v_cmp_lt_i32_e32 vcc, v183, v180
	s_waitcnt lgkmcnt(0)
	v_add_f32_e32 v8, v5, v8
	v_cndmask_b32_e32 v9, v183, v171, vcc
	v_cmp_gt_u32_e32 vcc, 2, v7
	v_lshlrev_b32_e32 v9, 2, v9
	s_nop 0
	v_cndmask_b32_e32 v5, v8, v5, vcc
	ds_bpermute_b32 v8, v9, v5
	v_cmp_lt_i32_e32 vcc, v184, v180
	s_waitcnt lgkmcnt(0)
	v_add_f32_e32 v8, v5, v8
	v_cndmask_b32_e32 v9, v184, v171, vcc
	v_cmp_gt_u32_e32 vcc, 4, v7
	v_lshlrev_b32_e32 v9, 2, v9
	s_nop 0
	v_cndmask_b32_e32 v5, v8, v5, vcc
	ds_bpermute_b32 v8, v9, v5
	v_cmp_lt_i32_e32 vcc, v185, v180
	s_waitcnt lgkmcnt(0)
	v_add_f32_e32 v8, v5, v8
	v_cndmask_b32_e32 v9, v185, v171, vcc
	v_cmp_gt_u32_e32 vcc, 8, v7
	v_lshlrev_b32_e32 v9, 2, v9
	s_nop 0
	v_cndmask_b32_e32 v5, v8, v5, vcc
	ds_bpermute_b32 v8, v9, v5
	v_cmp_lt_i32_e32 vcc, v186, v180
	s_waitcnt lgkmcnt(0)
	v_add_f32_e32 v8, v5, v8
	v_cndmask_b32_e32 v9, v186, v171, vcc
	v_cmp_gt_u32_e32 vcc, 16, v7
	v_lshlrev_b32_e32 v9, 2, v9
	s_nop 0
	v_cndmask_b32_e32 v8, v8, v5, vcc
	ds_bpermute_b32 v9, v9, v8
	v_ashrrev_i32_e32 v5, 6, v6
	v_cmp_eq_u32_e32 vcc, 63, v7
	s_waitcnt lgkmcnt(0)
	v_add_f32_e32 v9, v8, v9
	s_and_saveexec_b64 s[6:7], vcc
	v_lshlrev_b32_e32 v10, 2, v5
	ds_write_b32 v10, v9 offset:26624
	s_or_b64 exec, exec, s[6:7]
	v_cmp_gt_u32_e32 vcc, 32, v7
	v_lshrrev_b32_e32 v16, 5, v7
	s_waitcnt lgkmcnt(0)
	v_cndmask_b32_e32 v7, v9, v8, vcc
	s_barrier
	ds_read_b128 v[8:11], v137 offset:26624
	ds_read_b128 v[12:15], v137 offset:26640
	v_cmp_lt_i32_e32 vcc, 0, v5
	v_sub_f32_e32 v7, v7, v3
	s_andn2_b32 s6, 0x700, s8
	s_waitcnt lgkmcnt(1)
	v_cndmask_b32_e32 v8, 0, v8, vcc
	v_cmp_lt_i32_e32 vcc, 1, v5
	v_add_f32_e32 v7, v7, v8
	v_and_b32_e32 v17, 31, v6
	v_cndmask_b32_e32 v8, 0, v9, vcc
	v_cmp_lt_i32_e32 vcc, 2, v5
	v_add_f32_e32 v7, v7, v8
	v_lshlrev_b32_e32 v4, 2, v4
	v_cndmask_b32_e32 v8, 0, v10, vcc
	v_cmp_lt_i32_e32 vcc, 3, v5
	v_add_f32_e32 v7, v7, v8
	v_lshlrev_b32_e32 v136, 4, v16
	v_cndmask_b32_e32 v8, 0, v11, vcc
	v_cmp_lt_i32_e32 vcc, 4, v5
	v_add_f32_e32 v7, v7, v8
	v_mov_b32_e32 v100, 0
	s_waitcnt lgkmcnt(0)
	v_cndmask_b32_e32 v8, 0, v12, vcc
	v_cmp_lt_i32_e32 vcc, 5, v5
	v_add_f32_e32 v7, v7, v8
	v_lshl_add_u32 v12, v5, 5, s6
	v_cndmask_b32_e32 v8, 0, v13, vcc
	v_cmp_lt_i32_e32 vcc, 6, v5
	v_add_f32_e32 v7, v7, v8
	s_lshl_b32 s6, s8, 8
	v_cndmask_b32_e32 v8, 0, v14, vcc
	v_cmp_lt_i32_e32 vcc, 7, v5
	v_add_f32_e32 v7, v7, v8
	v_or_b32_e32 v96, v12, v17
	v_cndmask_b32_e32 v8, 0, v15, vcc
	v_add_f32_e32 v8, v7, v8
	v_pk_add_f32 v[0:1], v[0:1], v[8:9] op_sel_hi:[1,0]
	v_pk_add_f32 v[2:3], v[2:3], v[8:9] op_sel_hi:[1,0]
	s_and_b32 s10, s6, 0xf800
	ds_write_b128 v4, v[0:3]
	v_add_u32_e32 v0, s10, v96
	v_ashrrev_i32_e32 v1, 31, v0
	s_lshl_b32 s6, s8, 6
	v_lshlrev_b64 v[0:1], 9, v[0:1]
	s_and_b32 s11, s6, 0x1c0
	v_or_b32_e32 v0, s11, v0
	v_lshl_add_u64 v[88:89], v[0:1], 1, s[4:5]
	v_lshl_add_u64 v[0:1], v[88:89], 0, v[136:137]
	s_mov_b64 s[6:7], 0x30000000
	v_lshl_add_u64 v[2:3], v[0:1], 0, s[6:7]
	s_brev_b32 s6, 12
	v_add_co_u32_e32 v0, vcc, s6, v0
	s_waitcnt lgkmcnt(0)
	s_barrier
	v_addc_co_u32_e32 v1, vcc, 0, v1, vcc
	v_ashrrev_i32_e32 v0, 3, v6
	v_add_u32_e32 v2, s10, v0
	s_lshl_b32 s6, s9, 18
	v_ashrrev_i32_e32 v3, 31, v2
	s_add_u32 s6, s4, s6
	v_lshlrev_b64 v[2:3], 10, v[2:3]
	s_addc_u32 s7, s5, 0
	v_lshl_add_u64 v[2:3], s[4:5], 0, v[2:3]
	s_lshl_b32 s88, s11, 1
	v_lshlrev_b32_e32 v1, 4, v6
	v_lshl_add_u64 v[2:3], v[2:3], 0, s[88:89]
	v_and_b32_e32 v4, 0x70, v1
	v_mov_b32_e32 v5, v137
	v_ashrrev_i32_e32 v1, 31, v0
	v_lshl_add_u64 v[2:3], v[2:3], 0, v[4:5]
	v_lshlrev_b64 v[6:7], 12, v[0:1]
	s_brev_b32 s4, 36
	v_lshl_add_u64 v[6:7], s[6:7], 0, v[6:7]
	v_add_co_u32_e32 v8, vcc, s4, v2
	v_lshl_add_u64 v[6:7], v[6:7], 0, v[4:5]
	s_nop 0
	v_addc_co_u32_e32 v9, vcc, 0, v3, vcc
	s_brev_b32 s4, 44
	v_add_co_u32_e32 v10, vcc, s4, v6
	s_lshr_b32 s4, s8, 6
	s_nop 0
	v_addc_co_u32_e32 v11, vcc, 0, v7, vcc
	s_and_b32 s4, s4, 28
	s_sub_i32 s11, 32, s4
	s_mov_b64 s[4:5], 0x24000000
	v_lshl_add_u64 v[90:91], v[2:3], 0, s[4:5]
	s_mov_b64 s[4:5], 0x34000000
	v_lshlrev_b32_e32 v5, 2, v96
	v_lshl_add_u64 v[92:93], v[6:7], 0, s[4:5]
	s_movk_i32 s4, 0x90
	v_lshlrev_b32_e32 v1, 3, v16
	ds_read_b32 v97, v5
	v_mad_u64_u32 v[94:95], s[4:5], v0, s4, v[4:5]
	v_lshlrev_b32_e32 v95, 2, v16
	v_sub_u32_e32 v16, v136, v1
	v_mul_u32_u24_e32 v17, 0x90, v17
	v_cmp_lt_i32_e32 vcc, v177, v178
	v_mov_b32_e32 v14, v137
	v_mov_b32_e32 v15, v137
	v_cndmask_b32_e32 v0, v171, v177, vcc
	v_add_u32_e32 v16, v16, v17
	v_or_b32_e32 v98, 31, v12
	v_lshlrev_b32_e32 v99, 2, v0
	v_mov_b32_e32 v0, v137
	v_mov_b32_e32 v1, v137
	v_mov_b32_e32 v2, v137
	v_mov_b32_e32 v3, v137
	v_mov_b32_e32 v4, v137
	v_mov_b32_e32 v5, v137
	v_mov_b32_e32 v6, v137
	v_mov_b32_e32 v7, v137
	v_mov_b32_e32 v8, v137
	v_mov_b32_e32 v9, v137
	v_mov_b32_e32 v10, v137
	v_mov_b32_e32 v11, v137
	v_mov_b32_e32 v12, v137
	v_mov_b32_e32 v13, v137
	v_add_u32_e32 v101, v136, v17
	v_add_u32_e32 v102, 0x4000, v16
	v_add_u32_e32 v103, 0x5000, v16
	v_mov_b64_e32 v[30:31], v[14:15]
	s_mov_b32 s10, 0
	v_mov_b32_e32 v105, 0xf149f2ca
	s_mov_b64 s[4:5], 0
	v_mov_b32_e32 v104, v136
	v_mov_b64_e32 v[28:29], v[12:13]
	v_mov_b64_e32 v[26:27], v[10:11]
	v_mov_b64_e32 v[24:25], v[8:9]
	v_mov_b64_e32 v[22:23], v[6:7]
	v_mov_b64_e32 v[20:21], v[4:5]
	v_mov_b64_e32 v[18:19], v[2:3]
	v_mov_b64_e32 v[16:17], v[0:1]
	s_branch .LBB0_935
